# static s_setprio 1 for waves 4-7 during the P2 mixer work queue (on top of GEMM flips removed)
# baseline (speedup 1.0000x reference)
; __device__ __forceinline__ void phase_p2(const Params& p, int l) {
;   int* s_item = reinterpret_cast<int*>(smem + LDS_BYTES - 16);
;   int* cnt_s = p.ctr + 2 + l; int* cnt_m = p.ctr + 4 + l;
;   while (true) {
.LBB0_346:
	s_or_b64 exec, exec, s[0:1]
	s_mov_b32 s17, s69
	s_lshl_b64 s[0:1], s[16:17], 2
	s_mov_b64 s[20:21], s[16:17]
	v_readlane_b32 s4, v247, 7
	v_readlane_b32 s18, v247, 21
	v_readlane_b32 s19, v247, 22
	s_add_u32 s0, s18, s0
	s_addc_u32 s1, s19, s1
	s_add_u32 s44, s0, 8
	s_addc_u32 s45, s1, 0
	s_add_u32 s24, s0, 16
	v_writelane_b32 v246, s0, 13
	s_mul_i32 s2, s20, 3
	s_addc_u32 s25, s1, 0
	v_writelane_b32 v246, s1, 14
	v_writelane_b32 v246, s2, 15
	s_lshl_b32 s2, s20, 4
	v_writelane_b32 v246, s2, 16
	s_lshl_b32 s2, s20, 25
	v_writelane_b32 v246, s2, 17
	s_lshl_b32 s2, s20, 8
	v_writelane_b32 v246, s2, 18
	s_mov_b32 s2, s20
	v_readlane_b32 s8, v247, 11
	v_readlane_b32 s9, v247, 12
	v_readlane_b32 s10, v247, 13
	v_readlane_b32 s11, v247, 14
	v_readlane_b32 s12, v247, 15
	v_readlane_b32 s13, v247, 16
	v_readlane_b32 s14, v247, 17
	v_readlane_b32 s15, v247, 18
	v_readlane_b32 s16, v247, 19
	v_readlane_b32 s17, v247, 20
	v_writelane_b32 v246, s2, 11
	s_lshl_b64 s[0:1], s[20:21], 21
	s_mul_i32 s4, s20, 0x300000
	s_mul_i32 s68, s20, 0x600
	v_writelane_b32 v246, s3, 12
	s_lshl_b32 s2, s20, 7
	v_readlane_b32 s8, v248, 49
	v_readlane_b32 s14, v248, 55
	v_readlane_b32 s15, v248, 56
	s_add_u32 s0, s14, s0
	v_readlane_b32 s12, v248, 53
	v_writelane_b32 v246, s0, 19
	s_addc_u32 s0, s15, s1
	v_readlane_b32 s13, v248, 54
	v_writelane_b32 v246, s0, 20
	s_add_u32 s0, s12, s4
	v_readlane_b32 s10, v248, 51
	v_writelane_b32 v246, s0, 21
	s_addc_u32 s0, s13, 0
	v_readlane_b32 s11, v248, 52
	v_writelane_b32 v246, s0, 22
	s_add_u32 s0, s10, s26
	s_addc_u32 s1, s11, 0
	v_readlane_b32 s5, v247, 8
	v_writelane_b32 v246, s0, 23
	v_readlane_b32 s4, v247, 44
	v_readlane_b32 s5, v247, 45
	v_writelane_b32 v246, s1, 24
	s_lshl_b64 s[0:1], s[68:69], 2
	s_add_u32 s0, s4, s0
	s_addc_u32 s1, s5, s1
	s_mov_b32 s3, s69
	v_writelane_b32 v246, s0, 25
	s_waitcnt lgkmcnt(0)
	s_barrier
	v_writelane_b32 v246, s1, 26
	s_lshl_b64 s[0:1], s[2:3], 2
	v_readlane_b32 s2, v247, 46
	v_readlane_b32 s3, v247, 47
	s_add_u32 s0, s2, s0
	s_addc_u32 s1, s3, s1
	v_writelane_b32 v246, s0, 27
	v_readlane_b32 s6, v247, 9
	s_nop 0
	v_writelane_b32 v246, s1, 28
	v_writelane_b32 v246, s44, 29
	v_readlane_b32 s7, v247, 10
	v_readlane_b32 s9, v248, 50
	v_writelane_b32 v246, s45, 30
	v_writelane_b32 v246, s24, 31
	v_readlane_b32 s16, v248, 57
	v_readlane_b32 s17, v248, 58
	v_readlane_b32 s18, v248, 59
	v_readlane_b32 s19, v248, 60
	v_readlane_b32 s20, v248, 61
	v_readlane_b32 s21, v248, 62
	v_readlane_b32 s22, v248, 63
	v_readlane_b32 s23, v247, 0
	v_writelane_b32 v246, s25, 32
	v_readfirstlane_b32 s98, v188
	s_nop 3
	s_cmpk_gt_u32 s98, 0xff
	s_cbranch_scc0 .Lp2prio_skip
	s_setprio 1
.Lp2prio_skip:
	s_branch .LBB0_349

; #define LAS __attribute__((address_space(3)))
; __device__ __forceinline__ unsigned xb_xcc_id() { return (unsigned)__builtin_amdgcn_s_getreg((3 << 11) | 20) & 0xFu; }
; #define LAS __attribute__((address_space(3)))
; __device__ __forceinline__ void xcd_barrier(const XcdBarrier& b) {
;     asm volatile("s_waitcnt vmcnt(0)" ::: "memory");
;     __syncthreads();
;     if (threadIdx.x == 0) {
;         unsigned* bar = b.bar;
;         __builtin_amdgcn_s_waitcnt(0);
;         unsigned nloc = b.st[0], nx = b.st[1];
;         if (nloc == 0u) { xcd_barrier_complete(bar, b.x, nloc, nx); b.st[0] = nloc; b.st[1] = nx; }
; __device__ __forceinline__ void grid_bar(unsigned* bar) {
;   XcdBarrier b; b.bar = bar; b.x = xb_xcc_id(); b.st = (volatile LAS unsigned*)(smem + LDS_BYTES - 32);
;   xcd_barrier(b);
.LBB0_840:
	s_setprio 0
	s_getreg_b32 s2, hwreg(HW_REG_XCC_ID, 0, 4)
	s_waitcnt vmcnt(0)
	s_mov_b32 s61, s55
	s_barrier
	s_and_saveexec_b64 s[0:1], s[70:71]
	v_readlane_b32 s60, v248, 5
	s_cbranch_execz .LBB0_892
	v_readlane_b32 s3, v247, 33
	s_waitcnt vmcnt(0) expcnt(0) lgkmcnt(0)
	s_and_b32 s10, s2, 15
	v_mov_b32_e32 v0, s3
	ds_read_b32 v2, v0
	v_readlane_b32 s3, v247, 34
	s_waitcnt lgkmcnt(0)
	v_cmp_ne_u32_e32 vcc, 0, v2
	v_mov_b32_e32 v0, s3
	ds_read_b32 v0, v0
	s_cbranch_vccnz .LBB0_856
	s_mov_b32 s2, 1
	s_branch .LBB0_844
